# split-K combine (residual GEMM tails): all slab-slice loads of a task issued together instead of 22 serial load/wait round trips
# baseline (speedup 1.0000x reference)
; template <int NSL> __device__ __forceinline__ void slab_sum(const float* slab, int row, int c8, f32x4& s0, f32x4& s1) {
;     s0 = (f32x4){0.f, 0.f, 0.f, 0.f}; s1 = s0;
;     const __attribute__((address_space(1))) float* p = (const __attribute__((address_space(1))) float*)slab + (size_t)row * DM + c8;
; #pragma unroll
;     for (int s = 0; s < NSL; ++s) { s0 += *(const __attribute__((address_space(1))) f32x4*)(p + (size_t)s * TROWS * DM); s1 += *(const __attribute__((address_space(1))) f32x4*)(p + (size_t)s * TROWS * DM + 4); }
; }
; __global__ void __launch_bounds__(NWAVES * 64) fwd_kernel(Args args) {
;     ...
;               for (int wt = wave_ * G + (int)blockIdx.x; wt < TROWS * (DM / 8) / 64; wt += G * NWAVES) { const int i = wt * 64 + (ltid_ & 63); const int row = i / (DM / 8), c8 = (i % (DM / 8)) * 8;
;                   f32x4 s0, s1;
;                   if (K == DFF) slab_sum<DFF / KSPLIT>(slab, row, c8, s0, s1); else slab_sum<DM / KSPLIT>(slab, row, c8, s0, s1);
.LBB0_552:
	v_ashrrev_i32_e32 v2, 31, v0
	v_add_u32_sdwa v2, v0, v2 dst_sel:DWORD dst_unused:UNUSED_PAD src0_sel:DWORD src1_sel:BYTE_3
	v_ashrrev_i32_e32 v2, 8, v2
	v_mul_i32_i24_e32 v3, 0x100, v2
	v_sub_u32_e32 v3, v0, v3
	v_lshlrev_b32_e32 v4, 3, v3
	v_ashrrev_i32_e32 v3, 31, v2
	v_lshlrev_b64 v[6:7], 13, v[2:3]
	v_lshl_add_u64 v[6:7], s[4:5], 0, v[6:7]
	v_ashrrev_i32_e32 v5, 31, v4
	v_lshl_add_u64 v[6:7], v[4:5], 2, v[6:7]
	global_load_dwordx4 v[80:83], v[6:7], off
	global_load_dwordx4 v[84:87], v[6:7], off offset:16
	s_mov_b64 s[6:7], 0xa0000
	v_lshl_add_u64 v[18:19], v[6:7], 0, s[6:7]
	global_load_dwordx4 v[88:91], v[18:19], off
	global_load_dwordx4 v[92:95], v[18:19], off offset:16
	s_mov_b64 s[6:7], 0x140000
	v_lshl_add_u64 v[16:17], v[6:7], 0, s[6:7]
	global_load_dwordx4 v[96:99], v[16:17], off
	global_load_dwordx4 v[100:103], v[16:17], off offset:16
	s_mov_b64 s[6:7], 0x1e0000
	v_lshl_add_u64 v[18:19], v[6:7], 0, s[6:7]
	global_load_dwordx4 v[104:107], v[18:19], off
	global_load_dwordx4 v[108:111], v[18:19], off offset:16
	s_mov_b64 s[6:7], 0x280000
	v_lshl_add_u64 v[16:17], v[6:7], 0, s[6:7]
	global_load_dwordx4 v[112:115], v[16:17], off
	global_load_dwordx4 v[116:119], v[16:17], off offset:16
	s_mov_b64 s[6:7], 0x320000
	v_lshl_add_u64 v[18:19], v[6:7], 0, s[6:7]
	global_load_dwordx4 v[120:123], v[18:19], off
	global_load_dwordx4 v[124:127], v[18:19], off offset:16
	s_mov_b64 s[6:7], 0x3c0000
	v_lshl_add_u64 v[16:17], v[6:7], 0, s[6:7]
	global_load_dwordx4 v[128:131], v[16:17], off
	global_load_dwordx4 v[132:135], v[16:17], off offset:16
	s_mov_b64 s[6:7], 0x460000
	v_lshl_add_u64 v[18:19], v[6:7], 0, s[6:7]
	global_load_dwordx4 v[136:139], v[18:19], off
	global_load_dwordx4 v[140:143], v[18:19], off offset:16
	s_andn2_b64 vcc, exec, s[2:3]
	s_waitcnt vmcnt(14)
	v_pk_add_f32 v[14:15], v[80:81], 0 op_sel_hi:[1,0]
	v_pk_add_f32 v[12:13], v[82:83], 0 op_sel_hi:[1,0]
	v_pk_add_f32 v[10:11], v[84:85], 0 op_sel_hi:[1,0]
	v_pk_add_f32 v[8:9], v[86:87], 0 op_sel_hi:[1,0]
	s_waitcnt vmcnt(12)
	v_pk_add_f32 v[14:15], v[14:15], v[88:89]
	v_pk_add_f32 v[12:13], v[12:13], v[90:91]
	v_pk_add_f32 v[10:11], v[10:11], v[92:93]
	v_pk_add_f32 v[8:9], v[8:9], v[94:95]
	s_waitcnt vmcnt(10)
	v_pk_add_f32 v[14:15], v[14:15], v[96:97]
	v_pk_add_f32 v[12:13], v[12:13], v[98:99]
	v_pk_add_f32 v[10:11], v[10:11], v[100:101]
	v_pk_add_f32 v[8:9], v[8:9], v[102:103]
	s_waitcnt vmcnt(8)
	v_pk_add_f32 v[14:15], v[14:15], v[104:105]
	v_pk_add_f32 v[12:13], v[12:13], v[106:107]
	v_pk_add_f32 v[10:11], v[10:11], v[108:109]
	v_pk_add_f32 v[8:9], v[8:9], v[110:111]
	s_waitcnt vmcnt(6)
	v_pk_add_f32 v[14:15], v[14:15], v[112:113]
	v_pk_add_f32 v[12:13], v[12:13], v[114:115]
	v_pk_add_f32 v[10:11], v[10:11], v[116:117]
	v_pk_add_f32 v[8:9], v[8:9], v[118:119]
	s_waitcnt vmcnt(4)
	v_pk_add_f32 v[14:15], v[14:15], v[120:121]
	v_pk_add_f32 v[12:13], v[12:13], v[122:123]
	v_pk_add_f32 v[10:11], v[10:11], v[124:125]
	v_pk_add_f32 v[8:9], v[8:9], v[126:127]
	s_waitcnt vmcnt(2)
	v_pk_add_f32 v[14:15], v[14:15], v[128:129]
	v_pk_add_f32 v[12:13], v[12:13], v[130:131]
	v_pk_add_f32 v[10:11], v[10:11], v[132:133]
	v_pk_add_f32 v[8:9], v[8:9], v[134:135]
	s_waitcnt vmcnt(0)
	v_pk_add_f32 v[14:15], v[14:15], v[136:137]
	v_pk_add_f32 v[12:13], v[12:13], v[138:139]
	v_pk_add_f32 v[10:11], v[10:11], v[140:141]
	v_pk_add_f32 v[8:9], v[8:9], v[142:143]
	s_cbranch_vccnz .LBB0_554
; template <int NSL> __device__ __forceinline__ void slab_sum(const float* slab, int row, int c8, f32x4& s0, f32x4& s1) {
;     s0 = (f32x4){0.f, 0.f, 0.f, 0.f}; s1 = s0;
;     const __attribute__((address_space(1))) float* p = (const __attribute__((address_space(1))) float*)slab + (size_t)row * DM + c8;
; #pragma unroll
;     for (int s = 0; s < NSL; ++s) { s0 += *(const __attribute__((address_space(1))) f32x4*)(p + (size_t)s * TROWS * DM); s1 += *(const __attribute__((address_space(1))) f32x4*)(p + (size_t)s * TROWS * DM + 4); }
; }
	s_mov_b64 s[6:7], 0x500000
	v_lshl_add_u64 v[16:17], v[6:7], 0, s[6:7]
	global_load_dwordx4 v[80:83], v[16:17], off
	global_load_dwordx4 v[84:87], v[16:17], off offset:16
	s_mov_b64 s[6:7], 0x5a0000
	v_lshl_add_u64 v[18:19], v[6:7], 0, s[6:7]
	global_load_dwordx4 v[88:91], v[18:19], off
	global_load_dwordx4 v[92:95], v[18:19], off offset:16
	s_mov_b64 s[6:7], 0x640000
	v_lshl_add_u64 v[16:17], v[6:7], 0, s[6:7]
	global_load_dwordx4 v[96:99], v[16:17], off
	global_load_dwordx4 v[100:103], v[16:17], off offset:16
	s_mov_b64 s[6:7], 0x6e0000
	v_lshl_add_u64 v[18:19], v[6:7], 0, s[6:7]
	global_load_dwordx4 v[104:107], v[18:19], off
	global_load_dwordx4 v[108:111], v[18:19], off offset:16
	s_mov_b64 s[6:7], 0x780000
	v_lshl_add_u64 v[16:17], v[6:7], 0, s[6:7]
	global_load_dwordx4 v[112:115], v[16:17], off
	global_load_dwordx4 v[116:119], v[16:17], off offset:16
	s_mov_b64 s[6:7], 0x820000
	v_lshl_add_u64 v[18:19], v[6:7], 0, s[6:7]
	global_load_dwordx4 v[120:123], v[18:19], off
	global_load_dwordx4 v[124:127], v[18:19], off offset:16
	s_mov_b64 s[6:7], 0x8c0000
	v_lshl_add_u64 v[16:17], v[6:7], 0, s[6:7]
	global_load_dwordx4 v[128:131], v[16:17], off
	global_load_dwordx4 v[132:135], v[16:17], off offset:16
	s_mov_b64 s[6:7], 0x960000
	v_lshl_add_u64 v[18:19], v[6:7], 0, s[6:7]
	global_load_dwordx4 v[136:139], v[18:19], off
	global_load_dwordx4 v[140:143], v[18:19], off offset:16
	s_mov_b64 s[6:7], 0xa00000
	v_lshl_add_u64 v[16:17], v[6:7], 0, s[6:7]
	global_load_dwordx4 v[160:163], v[16:17], off
	global_load_dwordx4 v[164:167], v[16:17], off offset:16
	s_mov_b64 s[6:7], 0xaa0000
	v_lshl_add_u64 v[18:19], v[6:7], 0, s[6:7]
	global_load_dwordx4 v[168:171], v[18:19], off
	global_load_dwordx4 v[172:175], v[18:19], off offset:16
	s_mov_b64 s[6:7], 0xb40000
	v_lshl_add_u64 v[16:17], v[6:7], 0, s[6:7]
	global_load_dwordx4 v[176:179], v[16:17], off
	global_load_dwordx4 v[180:183], v[16:17], off offset:16
	s_mov_b64 s[6:7], 0xbe0000
	v_lshl_add_u64 v[18:19], v[6:7], 0, s[6:7]
	global_load_dwordx4 v[184:187], v[18:19], off
	global_load_dwordx4 v[188:191], v[18:19], off offset:16
	s_mov_b64 s[6:7], 0xc80000
	v_lshl_add_u64 v[16:17], v[6:7], 0, s[6:7]
	global_load_dwordx4 v[192:195], v[16:17], off
	global_load_dwordx4 v[196:199], v[16:17], off offset:16
	s_mov_b64 s[6:7], 0xd20000
	v_lshl_add_u64 v[18:19], v[6:7], 0, s[6:7]
	global_load_dwordx4 v[200:203], v[18:19], off
	global_load_dwordx4 v[204:207], v[18:19], off offset:16
	s_waitcnt vmcnt(26)
	v_pk_add_f32 v[14:15], v[14:15], v[80:81]
	v_pk_add_f32 v[12:13], v[12:13], v[82:83]
	v_pk_add_f32 v[10:11], v[10:11], v[84:85]
	v_pk_add_f32 v[8:9], v[8:9], v[86:87]
	s_waitcnt vmcnt(24)
	v_pk_add_f32 v[14:15], v[14:15], v[88:89]
	v_pk_add_f32 v[12:13], v[12:13], v[90:91]
	v_pk_add_f32 v[10:11], v[10:11], v[92:93]
	v_pk_add_f32 v[8:9], v[8:9], v[94:95]
	s_waitcnt vmcnt(22)
	v_pk_add_f32 v[14:15], v[14:15], v[96:97]
	v_pk_add_f32 v[12:13], v[12:13], v[98:99]
	v_pk_add_f32 v[10:11], v[10:11], v[100:101]
	v_pk_add_f32 v[8:9], v[8:9], v[102:103]
	s_waitcnt vmcnt(20)
	v_pk_add_f32 v[14:15], v[14:15], v[104:105]
	v_pk_add_f32 v[12:13], v[12:13], v[106:107]
	v_pk_add_f32 v[10:11], v[10:11], v[108:109]
	v_pk_add_f32 v[8:9], v[8:9], v[110:111]
	s_waitcnt vmcnt(18)
	v_pk_add_f32 v[14:15], v[14:15], v[112:113]
	v_pk_add_f32 v[12:13], v[12:13], v[114:115]
	v_pk_add_f32 v[10:11], v[10:11], v[116:117]
	v_pk_add_f32 v[8:9], v[8:9], v[118:119]
	s_waitcnt vmcnt(16)
	v_pk_add_f32 v[14:15], v[14:15], v[120:121]
	v_pk_add_f32 v[12:13], v[12:13], v[122:123]
	v_pk_add_f32 v[10:11], v[10:11], v[124:125]
	v_pk_add_f32 v[8:9], v[8:9], v[126:127]
	s_waitcnt vmcnt(14)
	v_pk_add_f32 v[14:15], v[14:15], v[128:129]
	v_pk_add_f32 v[12:13], v[12:13], v[130:131]
	v_pk_add_f32 v[10:11], v[10:11], v[132:133]
	v_pk_add_f32 v[8:9], v[8:9], v[134:135]
	s_waitcnt vmcnt(12)
	v_pk_add_f32 v[14:15], v[14:15], v[136:137]
	v_pk_add_f32 v[12:13], v[12:13], v[138:139]
	v_pk_add_f32 v[10:11], v[10:11], v[140:141]
	v_pk_add_f32 v[8:9], v[8:9], v[142:143]
	s_waitcnt vmcnt(10)
	v_pk_add_f32 v[14:15], v[14:15], v[160:161]
	v_pk_add_f32 v[12:13], v[12:13], v[162:163]
	v_pk_add_f32 v[10:11], v[10:11], v[164:165]
	v_pk_add_f32 v[8:9], v[8:9], v[166:167]
	s_waitcnt vmcnt(8)
	v_pk_add_f32 v[14:15], v[14:15], v[168:169]
	v_pk_add_f32 v[12:13], v[12:13], v[170:171]
	v_pk_add_f32 v[10:11], v[10:11], v[172:173]
	v_pk_add_f32 v[8:9], v[8:9], v[174:175]
	s_waitcnt vmcnt(6)
	v_pk_add_f32 v[14:15], v[14:15], v[176:177]
	v_pk_add_f32 v[12:13], v[12:13], v[178:179]
	v_pk_add_f32 v[10:11], v[10:11], v[180:181]
	v_pk_add_f32 v[8:9], v[8:9], v[182:183]
	s_waitcnt vmcnt(4)
	v_pk_add_f32 v[14:15], v[14:15], v[184:185]
	v_pk_add_f32 v[12:13], v[12:13], v[186:187]
	v_pk_add_f32 v[10:11], v[10:11], v[188:189]
	v_pk_add_f32 v[8:9], v[8:9], v[190:191]
	s_waitcnt vmcnt(2)
	v_pk_add_f32 v[14:15], v[14:15], v[192:193]
	v_pk_add_f32 v[12:13], v[12:13], v[194:195]
	v_pk_add_f32 v[10:11], v[10:11], v[196:197]
	v_pk_add_f32 v[8:9], v[8:9], v[198:199]
	s_waitcnt vmcnt(0)
	v_pk_add_f32 v[14:15], v[14:15], v[200:201]
	v_pk_add_f32 v[12:13], v[12:13], v[202:203]
	v_pk_add_f32 v[10:11], v[10:11], v[204:205]
	v_pk_add_f32 v[8:9], v[8:9], v[206:207]
